# P5: the 8 last-token (t = T-1) PR state copies are done by waves 2040..2047, one batch each, instead of all 8 by wave 2047
# speedup vs baseline: 1.0007x; 1.0007x over previous
; __device__ __forceinline__ f32x4 unpack4(u32x2 u) { return (f32x4){__uint_as_float(u.x << 16), __uint_as_float(u.x & 0xffff0000u), __uint_as_float(u.y << 16), __uint_as_float(u.y & 0xffff0000u)}; }
; template <int ph>
; __device__ __forceinline__ void run_phase(const Args& args, LAS unsigned char* lds, const int G, const int bx, const bool fin = true) {
;     ...
;                 if (t == T - 1) { float* dst = out + O_PSHIFT + (size_t)b * RP;
;                     for (int c = 4 * lane; c < RP; c += 256) *(f32x4*)(dst + c) = unpack4(*(const u32x2*)(PR + (size_t)row * RP + c)); }
.LBB0_692:
	s_add_i32 s98, s27, 0xfffff808
	s_cmp_lg_u32 s98, s28
	s_cbranch_scc1 .LBB0_696
	v_mad_i64_i32 v[0:1], s[28:29], s28, v75, v[64:65]
	s_mov_b64 s[28:29], 0
	s_sub_i32 s98, 0x7ff, s27
	s_mulk_i32 s98, 0x1a00
	s_mov_b32 s99, 0
	v_lshl_add_u64 v[2:3], v[62:63], 0, s[98:99]
	v_mov_b32_e32 v4, v17
	global_load_dwordx2 v[208:209], v[2:3], off
	global_load_dwordx2 v[210:211], v[2:3], off offset:512
	global_load_dwordx2 v[212:213], v[2:3], off offset:1024
	global_load_dwordx2 v[214:215], v[2:3], off offset:1536
	global_load_dwordx2 v[216:217], v[2:3], off offset:2048
	global_load_dwordx2 v[218:219], v[2:3], off offset:2560
	global_load_dwordx2 v[220:221], v[2:3], off offset:3072
	global_load_dwordx2 v[222:223], v[2:3], off offset:3584
	s_mov_b64 s[98:99], 0x1000
	v_lshl_add_u64 v[2:3], v[2:3], 0, s[98:99]
	global_load_dwordx2 v[224:225], v[2:3], off
	global_load_dwordx2 v[226:227], v[2:3], off offset:512
	global_load_dwordx2 v[230:231], v[2:3], off offset:1024
	global_load_dwordx2 v[232:233], v[2:3], off offset:1536
	global_load_dwordx2 v[234:235], v[2:3], off offset:2048
	s_waitcnt vmcnt(12)
	v_lshlrev_b32_e32 v6, 16, v208
	v_and_b32_e32 v7, 0xffff0000, v208
	v_lshlrev_b32_e32 v8, 16, v209
	v_and_b32_e32 v9, 0xffff0000, v209
	global_store_dwordx4 v[0:1], v[6:9], off
	s_waitcnt vmcnt(12)
	v_lshlrev_b32_e32 v10, 16, v210
	v_and_b32_e32 v11, 0xffff0000, v210
	v_lshlrev_b32_e32 v12, 16, v211
	v_and_b32_e32 v13, 0xffff0000, v211
	global_store_dwordx4 v[0:1], v[10:13], off offset:1024
	s_waitcnt vmcnt(12)
	v_lshlrev_b32_e32 v6, 16, v212
	v_and_b32_e32 v7, 0xffff0000, v212
	v_lshlrev_b32_e32 v8, 16, v213
	v_and_b32_e32 v9, 0xffff0000, v213
	global_store_dwordx4 v[0:1], v[6:9], off offset:2048
	s_waitcnt vmcnt(12)
	v_lshlrev_b32_e32 v10, 16, v214
	v_and_b32_e32 v11, 0xffff0000, v214
	v_lshlrev_b32_e32 v12, 16, v215
	v_and_b32_e32 v13, 0xffff0000, v215
	global_store_dwordx4 v[0:1], v[10:13], off offset:3072
	s_nop 1
	v_lshl_add_u64 v[0:1], v[0:1], 0, s[98:99]
	s_waitcnt vmcnt(12)
	v_lshlrev_b32_e32 v6, 16, v216
	v_and_b32_e32 v7, 0xffff0000, v216
	v_lshlrev_b32_e32 v8, 16, v217
	v_and_b32_e32 v9, 0xffff0000, v217
	global_store_dwordx4 v[0:1], v[6:9], off
	s_waitcnt vmcnt(12)
	v_lshlrev_b32_e32 v10, 16, v218
	v_and_b32_e32 v11, 0xffff0000, v218
	v_lshlrev_b32_e32 v12, 16, v219
	v_and_b32_e32 v13, 0xffff0000, v219
	global_store_dwordx4 v[0:1], v[10:13], off offset:1024
	s_waitcnt vmcnt(12)
	v_lshlrev_b32_e32 v6, 16, v220
	v_and_b32_e32 v7, 0xffff0000, v220
	v_lshlrev_b32_e32 v8, 16, v221
	v_and_b32_e32 v9, 0xffff0000, v221
	global_store_dwordx4 v[0:1], v[6:9], off offset:2048
	s_waitcnt vmcnt(12)
	v_lshlrev_b32_e32 v10, 16, v222
	v_and_b32_e32 v11, 0xffff0000, v222
	v_lshlrev_b32_e32 v12, 16, v223
	v_and_b32_e32 v13, 0xffff0000, v223
	global_store_dwordx4 v[0:1], v[10:13], off offset:3072
	s_nop 1
	v_lshl_add_u64 v[0:1], v[0:1], 0, s[98:99]
	s_waitcnt vmcnt(12)
	v_lshlrev_b32_e32 v6, 16, v224
	v_and_b32_e32 v7, 0xffff0000, v224
	v_lshlrev_b32_e32 v8, 16, v225
	v_and_b32_e32 v9, 0xffff0000, v225
	global_store_dwordx4 v[0:1], v[6:9], off
	s_waitcnt vmcnt(12)
	v_lshlrev_b32_e32 v10, 16, v226
	v_and_b32_e32 v11, 0xffff0000, v226
	v_lshlrev_b32_e32 v12, 16, v227
	v_and_b32_e32 v13, 0xffff0000, v227
	global_store_dwordx4 v[0:1], v[10:13], off offset:1024
	s_waitcnt vmcnt(12)
	v_lshlrev_b32_e32 v6, 16, v230
	v_and_b32_e32 v7, 0xffff0000, v230
	v_lshlrev_b32_e32 v8, 16, v231
	v_and_b32_e32 v9, 0xffff0000, v231
	global_store_dwordx4 v[0:1], v[6:9], off offset:2048
	s_waitcnt vmcnt(12)
	v_lshlrev_b32_e32 v10, 16, v232
	v_and_b32_e32 v11, 0xffff0000, v232
	v_lshlrev_b32_e32 v12, 16, v233
	v_and_b32_e32 v13, 0xffff0000, v233
	global_store_dwordx4 v[0:1], v[10:13], off offset:3072
	s_nop 1
	v_lshl_add_u64 v[0:1], v[0:1], 0, s[98:99]
	s_waitcnt vmcnt(12)
	v_lshlrev_b32_e32 v6, 16, v234
	v_and_b32_e32 v7, 0xffff0000, v234
	v_lshlrev_b32_e32 v8, 16, v235
	v_and_b32_e32 v9, 0xffff0000, v235
	global_store_dwordx4 v[0:1], v[6:9], off
